# P5 epilogue re-written (one v_max per value, packed squares, in-place bf16 packing) + XCD-local seams (3us stagger) + P4/P6' epilogue rewrites
# speedup vs baseline: 1.0013x; 1.0013x over previous
.LBB0_510:
	s_lshl_b32 s17, s24, 7
	s_lshl_b32 s21, s25, 2
	s_add_i32 s17, s17, s21
	s_or_b32 s24, s17, s50
	s_ashr_i32 s25, s24, 31
	s_lshl_b64 s[24:25], s[24:25], 15
	s_add_u32 s24, s70, s24
	s_addc_u32 s25, s71, s25
	v_add_u32_e32 v166, s8, v136
	v_add_u32_e32 v166, v166, v160
	v_max_f32_e32 v124, 0, v124
	v_max_f32_e32 v125, 0, v125
	v_max_f32_e32 v126, 0, v126
	v_max_f32_e32 v127, 0, v127
	v_max_f32_e32 v120, 0, v120
	v_max_f32_e32 v121, 0, v121
	v_max_f32_e32 v122, 0, v122
	v_max_f32_e32 v123, 0, v123
	v_pk_mul_f32 v[124:125], v[124:125], v[124:125]
	v_pk_mul_f32 v[126:127], v[126:127], v[126:127]
	v_pk_mul_f32 v[120:121], v[120:121], v[120:121]
	v_pk_mul_f32 v[122:123], v[122:123], v[122:123]
	v_cvt_pk_bf16_f32 v124, v124, v125
	v_cvt_pk_bf16_f32 v125, v126, v127
	v_cvt_pk_bf16_f32 v126, v120, v121
	v_cvt_pk_bf16_f32 v127, v122, v123
	s_mov_b32 s98, s24
	s_mov_b32 s99, s25
	s_nop 0
	global_store_dwordx4 v166, v[124:127], s[98:99]
	v_max_f32_e32 v116, 0, v116
	v_max_f32_e32 v117, 0, v117
	v_max_f32_e32 v118, 0, v118
	v_max_f32_e32 v119, 0, v119
	v_max_f32_e32 v112, 0, v112
	v_max_f32_e32 v113, 0, v113
	v_max_f32_e32 v114, 0, v114
	v_max_f32_e32 v115, 0, v115
	v_pk_mul_f32 v[116:117], v[116:117], v[116:117]
	v_pk_mul_f32 v[118:119], v[118:119], v[118:119]
	v_pk_mul_f32 v[112:113], v[112:113], v[112:113]
	v_pk_mul_f32 v[114:115], v[114:115], v[114:115]
	v_cvt_pk_bf16_f32 v116, v116, v117
	v_cvt_pk_bf16_f32 v117, v118, v119
	v_cvt_pk_bf16_f32 v118, v112, v113
	v_cvt_pk_bf16_f32 v119, v114, v115
	s_add_u32 s98, s24, 0x10000
	s_addc_u32 s99, s25, 0
	s_nop 0
	global_store_dwordx4 v166, v[116:119], s[98:99]
	v_max_f32_e32 v108, 0, v108
	v_max_f32_e32 v109, 0, v109
	v_max_f32_e32 v110, 0, v110
	v_max_f32_e32 v111, 0, v111
	v_max_f32_e32 v104, 0, v104
	v_max_f32_e32 v105, 0, v105
	v_max_f32_e32 v106, 0, v106
	v_max_f32_e32 v107, 0, v107
	v_pk_mul_f32 v[108:109], v[108:109], v[108:109]
	v_pk_mul_f32 v[110:111], v[110:111], v[110:111]
	v_pk_mul_f32 v[104:105], v[104:105], v[104:105]
	v_pk_mul_f32 v[106:107], v[106:107], v[106:107]
	v_cvt_pk_bf16_f32 v108, v108, v109
	v_cvt_pk_bf16_f32 v109, v110, v111
	v_cvt_pk_bf16_f32 v110, v104, v105
	v_cvt_pk_bf16_f32 v111, v106, v107
	s_add_u32 s98, s24, 0x800
	s_addc_u32 s99, s25, 0
	s_nop 0
	global_store_dwordx4 v166, v[108:111], s[98:99]
	v_max_f32_e32 v100, 0, v100
	v_max_f32_e32 v101, 0, v101
	v_max_f32_e32 v102, 0, v102
	v_max_f32_e32 v103, 0, v103
	v_max_f32_e32 v96, 0, v96
	v_max_f32_e32 v97, 0, v97
	v_max_f32_e32 v98, 0, v98
	v_max_f32_e32 v99, 0, v99
	v_pk_mul_f32 v[100:101], v[100:101], v[100:101]
	v_pk_mul_f32 v[102:103], v[102:103], v[102:103]
	v_pk_mul_f32 v[96:97], v[96:97], v[96:97]
	v_pk_mul_f32 v[98:99], v[98:99], v[98:99]
	v_cvt_pk_bf16_f32 v100, v100, v101
	v_cvt_pk_bf16_f32 v101, v102, v103
	v_cvt_pk_bf16_f32 v102, v96, v97
	v_cvt_pk_bf16_f32 v103, v98, v99
	s_add_u32 s98, s24, 0x10800
	s_addc_u32 s99, s25, 0
	s_nop 0
	global_store_dwordx4 v166, v[100:103], s[98:99]
	v_max_f32_e32 v92, 0, v92
	v_max_f32_e32 v93, 0, v93
	v_max_f32_e32 v94, 0, v94
	v_max_f32_e32 v95, 0, v95
	v_max_f32_e32 v88, 0, v88
	v_max_f32_e32 v89, 0, v89
	v_max_f32_e32 v90, 0, v90
	v_max_f32_e32 v91, 0, v91
	v_pk_mul_f32 v[92:93], v[92:93], v[92:93]
	v_pk_mul_f32 v[94:95], v[94:95], v[94:95]
	v_pk_mul_f32 v[88:89], v[88:89], v[88:89]
	v_pk_mul_f32 v[90:91], v[90:91], v[90:91]
	v_cvt_pk_bf16_f32 v92, v92, v93
	v_cvt_pk_bf16_f32 v93, v94, v95
	v_cvt_pk_bf16_f32 v94, v88, v89
	v_cvt_pk_bf16_f32 v95, v90, v91
	s_add_u32 s98, s24, 0x1000
	s_addc_u32 s99, s25, 0
	s_nop 0
	global_store_dwordx4 v166, v[92:95], s[98:99]
	v_max_f32_e32 v84, 0, v84
	v_max_f32_e32 v85, 0, v85
	v_max_f32_e32 v86, 0, v86
	v_max_f32_e32 v87, 0, v87
	v_max_f32_e32 v80, 0, v80
	v_max_f32_e32 v81, 0, v81
	v_max_f32_e32 v82, 0, v82
	v_max_f32_e32 v83, 0, v83
	v_pk_mul_f32 v[84:85], v[84:85], v[84:85]
	v_pk_mul_f32 v[86:87], v[86:87], v[86:87]
	v_pk_mul_f32 v[80:81], v[80:81], v[80:81]
	v_pk_mul_f32 v[82:83], v[82:83], v[82:83]
	v_cvt_pk_bf16_f32 v84, v84, v85
	v_cvt_pk_bf16_f32 v85, v86, v87
	v_cvt_pk_bf16_f32 v86, v80, v81
	v_cvt_pk_bf16_f32 v87, v82, v83
	s_add_u32 s98, s24, 0x11000
	s_addc_u32 s99, s25, 0
	s_nop 0
	global_store_dwordx4 v166, v[84:87], s[98:99]
	v_max_f32_e32 v76, 0, v76
	v_max_f32_e32 v77, 0, v77
	v_max_f32_e32 v78, 0, v78
	v_max_f32_e32 v79, 0, v79
	v_max_f32_e32 v72, 0, v72
	v_max_f32_e32 v73, 0, v73
	v_max_f32_e32 v74, 0, v74
	v_max_f32_e32 v75, 0, v75
	v_pk_mul_f32 v[76:77], v[76:77], v[76:77]
	v_pk_mul_f32 v[78:79], v[78:79], v[78:79]
	v_pk_mul_f32 v[72:73], v[72:73], v[72:73]
	v_pk_mul_f32 v[74:75], v[74:75], v[74:75]
	v_cvt_pk_bf16_f32 v76, v76, v77
	v_cvt_pk_bf16_f32 v77, v78, v79
	v_cvt_pk_bf16_f32 v78, v72, v73
	v_cvt_pk_bf16_f32 v79, v74, v75
	s_add_u32 s98, s24, 0x1800
	s_addc_u32 s99, s25, 0
	s_nop 0
	global_store_dwordx4 v166, v[76:79], s[98:99]
	v_max_f32_e32 v68, 0, v68
	v_max_f32_e32 v69, 0, v69
	v_max_f32_e32 v70, 0, v70
	v_max_f32_e32 v71, 0, v71
	v_max_f32_e32 v64, 0, v64
	v_max_f32_e32 v65, 0, v65
	v_max_f32_e32 v66, 0, v66
	v_max_f32_e32 v67, 0, v67
	v_pk_mul_f32 v[68:69], v[68:69], v[68:69]
	v_pk_mul_f32 v[70:71], v[70:71], v[70:71]
	v_pk_mul_f32 v[64:65], v[64:65], v[64:65]
	v_pk_mul_f32 v[66:67], v[66:67], v[66:67]
	v_cvt_pk_bf16_f32 v68, v68, v69
	v_cvt_pk_bf16_f32 v69, v70, v71
	v_cvt_pk_bf16_f32 v70, v64, v65
	v_cvt_pk_bf16_f32 v71, v66, v67
	s_add_u32 s98, s24, 0x11800
	s_addc_u32 s99, s25, 0
	s_nop 0
	global_store_dwordx4 v166, v[68:71], s[98:99]
	v_max_f32_e32 v60, 0, v60
	v_max_f32_e32 v61, 0, v61
	v_max_f32_e32 v62, 0, v62
	v_max_f32_e32 v63, 0, v63
	v_max_f32_e32 v56, 0, v56
	v_max_f32_e32 v57, 0, v57
	v_max_f32_e32 v58, 0, v58
	v_max_f32_e32 v59, 0, v59
	v_pk_mul_f32 v[60:61], v[60:61], v[60:61]
	v_pk_mul_f32 v[62:63], v[62:63], v[62:63]
	v_pk_mul_f32 v[56:57], v[56:57], v[56:57]
	v_pk_mul_f32 v[58:59], v[58:59], v[58:59]
	v_cvt_pk_bf16_f32 v60, v60, v61
	v_cvt_pk_bf16_f32 v61, v62, v63
	v_cvt_pk_bf16_f32 v62, v56, v57
	v_cvt_pk_bf16_f32 v63, v58, v59
	s_add_u32 s98, s24, 0x4000
	s_addc_u32 s99, s25, 0
	s_nop 0
	global_store_dwordx4 v166, v[60:63], s[98:99]
	v_max_f32_e32 v52, 0, v52
	v_max_f32_e32 v53, 0, v53
	v_max_f32_e32 v54, 0, v54
	v_max_f32_e32 v55, 0, v55
	v_max_f32_e32 v48, 0, v48
	v_max_f32_e32 v49, 0, v49
	v_max_f32_e32 v50, 0, v50
	v_max_f32_e32 v51, 0, v51
	v_pk_mul_f32 v[52:53], v[52:53], v[52:53]
	v_pk_mul_f32 v[54:55], v[54:55], v[54:55]
	v_pk_mul_f32 v[48:49], v[48:49], v[48:49]
	v_pk_mul_f32 v[50:51], v[50:51], v[50:51]
	v_cvt_pk_bf16_f32 v52, v52, v53
	v_cvt_pk_bf16_f32 v53, v54, v55
	v_cvt_pk_bf16_f32 v54, v48, v49
	v_cvt_pk_bf16_f32 v55, v50, v51
	s_add_u32 s98, s24, 0x14000
	s_addc_u32 s99, s25, 0
	s_nop 0
	global_store_dwordx4 v166, v[52:55], s[98:99]
	v_max_f32_e32 v44, 0, v44
	v_max_f32_e32 v45, 0, v45
	v_max_f32_e32 v46, 0, v46
	v_max_f32_e32 v47, 0, v47
	v_max_f32_e32 v40, 0, v40
	v_max_f32_e32 v41, 0, v41
	v_max_f32_e32 v42, 0, v42
	v_max_f32_e32 v43, 0, v43
	v_pk_mul_f32 v[44:45], v[44:45], v[44:45]
	v_pk_mul_f32 v[46:47], v[46:47], v[46:47]
	v_pk_mul_f32 v[40:41], v[40:41], v[40:41]
	v_pk_mul_f32 v[42:43], v[42:43], v[42:43]
	v_cvt_pk_bf16_f32 v44, v44, v45
	v_cvt_pk_bf16_f32 v45, v46, v47
	v_cvt_pk_bf16_f32 v46, v40, v41
	v_cvt_pk_bf16_f32 v47, v42, v43
	s_add_u32 s98, s24, 0x4800
	s_addc_u32 s99, s25, 0
	s_nop 0
	global_store_dwordx4 v166, v[44:47], s[98:99]
	v_max_f32_e32 v36, 0, v36
	v_max_f32_e32 v37, 0, v37
	v_max_f32_e32 v38, 0, v38
	v_max_f32_e32 v39, 0, v39
	v_max_f32_e32 v32, 0, v32
	v_max_f32_e32 v33, 0, v33
	v_max_f32_e32 v34, 0, v34
	v_max_f32_e32 v35, 0, v35
	v_pk_mul_f32 v[36:37], v[36:37], v[36:37]
	v_pk_mul_f32 v[38:39], v[38:39], v[38:39]
	v_pk_mul_f32 v[32:33], v[32:33], v[32:33]
	v_pk_mul_f32 v[34:35], v[34:35], v[34:35]
	v_cvt_pk_bf16_f32 v36, v36, v37
	v_cvt_pk_bf16_f32 v37, v38, v39
	v_cvt_pk_bf16_f32 v38, v32, v33
	v_cvt_pk_bf16_f32 v39, v34, v35
	s_add_u32 s98, s24, 0x14800
	s_addc_u32 s99, s25, 0
	s_nop 0
	global_store_dwordx4 v166, v[36:39], s[98:99]
	v_max_f32_e32 v28, 0, v28
	v_max_f32_e32 v29, 0, v29
	v_max_f32_e32 v30, 0, v30
	v_max_f32_e32 v31, 0, v31
	v_max_f32_e32 v24, 0, v24
	v_max_f32_e32 v25, 0, v25
	v_max_f32_e32 v26, 0, v26
	v_max_f32_e32 v27, 0, v27
	v_pk_mul_f32 v[28:29], v[28:29], v[28:29]
	v_pk_mul_f32 v[30:31], v[30:31], v[30:31]
	v_pk_mul_f32 v[24:25], v[24:25], v[24:25]
	v_pk_mul_f32 v[26:27], v[26:27], v[26:27]
	v_cvt_pk_bf16_f32 v28, v28, v29
	v_cvt_pk_bf16_f32 v29, v30, v31
	v_cvt_pk_bf16_f32 v30, v24, v25
	v_cvt_pk_bf16_f32 v31, v26, v27
	s_add_u32 s98, s24, 0x5000
	s_addc_u32 s99, s25, 0
	s_nop 0
	global_store_dwordx4 v166, v[28:31], s[98:99]
	v_max_f32_e32 v20, 0, v20
	v_max_f32_e32 v21, 0, v21
	v_max_f32_e32 v22, 0, v22
	v_max_f32_e32 v23, 0, v23
	v_max_f32_e32 v16, 0, v16
	v_max_f32_e32 v17, 0, v17
	v_max_f32_e32 v18, 0, v18
	v_max_f32_e32 v19, 0, v19
	v_pk_mul_f32 v[20:21], v[20:21], v[20:21]
	v_pk_mul_f32 v[22:23], v[22:23], v[22:23]
	v_pk_mul_f32 v[16:17], v[16:17], v[16:17]
	v_pk_mul_f32 v[18:19], v[18:19], v[18:19]
	v_cvt_pk_bf16_f32 v20, v20, v21
	v_cvt_pk_bf16_f32 v21, v22, v23
	v_cvt_pk_bf16_f32 v22, v16, v17
	v_cvt_pk_bf16_f32 v23, v18, v19
	s_add_u32 s98, s24, 0x15000
	s_addc_u32 s99, s25, 0
	s_nop 0
	global_store_dwordx4 v166, v[20:23], s[98:99]
	v_max_f32_e32 v12, 0, v12
	v_max_f32_e32 v13, 0, v13
	v_max_f32_e32 v14, 0, v14
	v_max_f32_e32 v15, 0, v15
	v_max_f32_e32 v8, 0, v8
	v_max_f32_e32 v9, 0, v9
	v_max_f32_e32 v10, 0, v10
	v_max_f32_e32 v11, 0, v11
	v_pk_mul_f32 v[12:13], v[12:13], v[12:13]
	v_pk_mul_f32 v[14:15], v[14:15], v[14:15]
	v_pk_mul_f32 v[8:9], v[8:9], v[8:9]
	v_pk_mul_f32 v[10:11], v[10:11], v[10:11]
	v_cvt_pk_bf16_f32 v12, v12, v13
	v_cvt_pk_bf16_f32 v13, v14, v15
	v_cvt_pk_bf16_f32 v14, v8, v9
	v_cvt_pk_bf16_f32 v15, v10, v11
	s_add_u32 s98, s24, 0x5800
	s_addc_u32 s99, s25, 0
	s_nop 0
	global_store_dwordx4 v166, v[12:15], s[98:99]
	v_max_f32_e32 v4, 0, v4
	v_max_f32_e32 v5, 0, v5
	v_max_f32_e32 v6, 0, v6
	v_max_f32_e32 v7, 0, v7
	v_max_f32_e32 v0, 0, v0
	v_max_f32_e32 v1, 0, v1
	v_max_f32_e32 v2, 0, v2
	v_max_f32_e32 v3, 0, v3
	v_pk_mul_f32 v[4:5], v[4:5], v[4:5]
	v_pk_mul_f32 v[6:7], v[6:7], v[6:7]
	v_pk_mul_f32 v[0:1], v[0:1], v[0:1]
	v_pk_mul_f32 v[2:3], v[2:3], v[2:3]
	v_cvt_pk_bf16_f32 v4, v4, v5
	v_cvt_pk_bf16_f32 v5, v6, v7
	v_cvt_pk_bf16_f32 v6, v0, v1
	v_cvt_pk_bf16_f32 v7, v2, v3
	s_add_u32 s98, s24, 0x15800
	s_addc_u32 s99, s25, 0
	s_nop 0
	global_store_dwordx4 v166, v[4:7], s[98:99]
	s_and_b64 vcc, exec, s[4:5]
	s_mov_b64 s[4:5], -1
	s_cbranch_vccnz .LBB0_497
	s_and_b64 vcc, exec, s[0:1]
	s_cbranch_vccnz .LBB0_496
	s_barrier
	s_branch .LBB0_496
